# tr_item gain loads batched (16 loads, one wait) in P2 weight conversion, on top of v6
# speedup vs baseline: 1.0013x; 1.0013x over previous
; DI void tr_item(const float* W, int ldw, int k0, int col, const float* gain, bf16* dst_n0, int K, LAS float* scr, int lane) {
;     ...
;     f32x4 v[16];
; #pragma unroll
;     for (int i = 0; i < 16; ++i) { v[i] = (f32x4){0.f, 0.f, 0.f, 0.f}; if (col >= 0) v[i] = *(const f32x4*)(W + (size_t)(k0 + 4 * i + kr) * ldw + col); }
;     if (gain) {
; #pragma unroll
;         for (int i = 0; i < 16; ++i) v[i] *= gain[k0 + 4 * i + kr];
; DI void convert_weights(const P& p, ldsp lds, int l, int part, int nb, int bi, int wv) {
;     ...
;         if (r < IGU) { const int nb = r % (NGU / 64), kb = r / (NGU / 64); const int n = nb * 64, pp = n >> 8, sg = (n >> 7) & 1, j = n & 127;
;             tr_item((sg ? p.w_up : p.w_gate) + (size_t)l * DM * FF, FF, kb * 64, 128 * pp + j + nl, p.ffn_norm + l * DM, (bf16*)(wl + OWGU) + (size_t)n * DM, DM, scr, lane); continue; } r -= IGU;
.LBB0_258:
	s_andn2_saveexec_b64 s[50:51], s[26:27]
	s_cbranch_execz .LBB0_262
	v_add_u16_e32 v0, 0xf080, v0
	v_mul_u32_u24_e32 v2, 0xba2f, v0
	v_lshrrev_b32_e32 v4, 23, v2
	v_mul_lo_u16_e32 v2, 0xb0, v4
	v_sub_u16_e32 v67, v0, v2
	v_and_b32_e32 v0, 2, v67
	v_cmp_eq_u32_e32 vcc, 0, v0
	v_mov_b32_e32 v0, 0x88
	v_mov_b32_e32 v2, 0x80
	v_readlane_b32 s26, v252, 3
	v_cndmask_b32_e32 v0, v0, v2, vcc
	v_readlane_b32 s27, v252, 4
	v_lshlrev_b16_e32 v66, 6, v4
	v_lshlrev_b32_e32 v4, 5, v67
	v_lshl_add_u64 v[2:3], s[26:27], 0, v[0:1]
	global_load_dwordx2 v[2:3], v[2:3], off
	v_lshlrev_b32_e32 v0, 6, v67
	v_and_b32_e32 v0, 64, v0
	v_and_b32_e32 v4, 0x1f80, v4
	v_or_b32_e32 v83, v73, v66
	v_or3_b32 v0, v4, v0, v71
	v_mul_u32_u24_e32 v5, 0x1600, v83
	v_lshlrev_b32_e32 v0, 2, v0
	s_mov_b32 s26, 0x16000
	s_waitcnt vmcnt(0)
	v_lshl_add_u64 v[2:3], v[2:3], 0, s[16:17]
	v_lshl_add_u64 v[2:3], v[2:3], 0, v[0:1]
	v_lshlrev_b32_e32 v0, 2, v5
	v_lshl_add_u64 v[58:59], v[2:3], 0, v[0:1]
	v_add_co_u32_e32 v2, vcc, s26, v58
	s_mov_b32 s26, 0x2c000
	s_nop 0
	v_addc_co_u32_e32 v3, vcc, 0, v59, vcc
	v_add_co_u32_e32 v4, vcc, s26, v58
	s_mov_b32 s26, 0x42000
	s_nop 0
	v_addc_co_u32_e32 v5, vcc, 0, v59, vcc
	v_add_co_u32_e32 v6, vcc, s26, v58
	s_mov_b32 s26, 0x58000
	s_nop 0
	v_addc_co_u32_e32 v7, vcc, 0, v59, vcc
	v_add_co_u32_e32 v8, vcc, s26, v58
	s_mov_b32 s26, 0x6e000
	s_nop 0
	v_addc_co_u32_e32 v9, vcc, 0, v59, vcc
	v_add_co_u32_e32 v10, vcc, s26, v58
	s_mov_b32 s26, 0x84000
	s_nop 0
	v_addc_co_u32_e32 v11, vcc, 0, v59, vcc
	v_add_co_u32_e32 v12, vcc, s26, v58
	s_mov_b32 s26, 0x9a000
	s_nop 0
	v_addc_co_u32_e32 v13, vcc, 0, v59, vcc
	v_add_co_u32_e32 v42, vcc, s26, v58
	s_mov_b32 s26, 0xb0000
	s_nop 0
	v_addc_co_u32_e32 v43, vcc, 0, v59, vcc
	v_add_co_u32_e32 v44, vcc, s26, v58
	s_mov_b32 s26, 0xc6000
	s_nop 0
	v_addc_co_u32_e32 v45, vcc, 0, v59, vcc
	v_add_co_u32_e32 v46, vcc, s26, v58
	s_mov_b32 s26, 0xdc000
	s_nop 0
	v_addc_co_u32_e32 v47, vcc, 0, v59, vcc
	v_add_co_u32_e32 v48, vcc, s26, v58
	s_mov_b32 s26, 0xf2000
	s_nop 0
	v_addc_co_u32_e32 v49, vcc, 0, v59, vcc
	global_load_dwordx4 v[38:41], v[58:59], off
	global_load_dwordx4 v[34:37], v[2:3], off
	global_load_dwordx4 v[30:33], v[4:5], off
	global_load_dwordx4 v[26:29], v[6:7], off
	global_load_dwordx4 v[22:25], v[8:9], off
	global_load_dwordx4 v[18:21], v[10:11], off
	global_load_dwordx4 v[14:17], v[12:13], off
	s_nop 0
	global_load_dwordx4 v[10:13], v[42:43], off
	global_load_dwordx4 v[6:9], v[44:45], off
	global_load_dwordx4 v[2:5], v[46:47], off
	v_add_co_u32_e32 v42, vcc, s26, v58
	s_mov_b32 s26, 0x108000
	s_nop 0
	v_addc_co_u32_e32 v43, vcc, 0, v59, vcc
	v_add_co_u32_e32 v50, vcc, s26, v58
	global_load_dwordx4 v[46:49], v[48:49], off
	s_nop 0
	global_load_dwordx4 v[42:45], v[42:43], off
	v_addc_co_u32_e32 v51, vcc, 0, v59, vcc
	v_add_co_u32_e32 v52, vcc, 0x11e000, v58
	v_readlane_b32 s26, v253, 12
	s_nop 0
	v_addc_co_u32_e32 v53, vcc, 0, v59, vcc
	v_add_co_u32_e32 v60, vcc, 0x134000, v58
	global_load_dwordx4 v[54:57], v[50:51], off
	s_nop 0
	global_load_dwordx4 v[50:53], v[52:53], off
	v_addc_co_u32_e32 v61, vcc, 0, v59, vcc
	v_add_co_u32_e32 v58, vcc, 0x14a000, v58
	v_readlane_b32 s27, v253, 13
	s_nop 0
	v_addc_co_u32_e32 v59, vcc, 0, v59, vcc
	global_load_dwordx4 v[62:65], v[60:61], off
	s_nop 0
	global_load_dwordx4 v[58:61], v[58:59], off
	s_andn2_b64 vcc, exec, s[26:27]
	s_cbranch_vccnz .LBB0_261
	v_lshlrev_b32_e32 v83, 2, v83
	global_load_dword v160, v83, s[18:19]
	global_load_dword v161, v83, s[18:19] offset:16
	global_load_dword v162, v83, s[18:19] offset:32
	global_load_dword v163, v83, s[18:19] offset:48
	global_load_dword v164, v83, s[18:19] offset:64
	global_load_dword v165, v83, s[18:19] offset:80
	global_load_dword v166, v83, s[18:19] offset:96
	global_load_dword v167, v83, s[18:19] offset:112
	global_load_dword v168, v83, s[18:19] offset:128
	global_load_dword v169, v83, s[18:19] offset:144
	global_load_dword v170, v83, s[18:19] offset:160
	global_load_dword v171, v83, s[18:19] offset:176
	global_load_dword v172, v83, s[18:19] offset:192
	global_load_dword v173, v83, s[18:19] offset:208
	global_load_dword v174, v83, s[18:19] offset:224
	global_load_dword v175, v83, s[18:19] offset:240
	s_waitcnt vmcnt(0)
	v_pk_mul_f32 v[40:41], v[40:41], v[160:161] op_sel_hi:[1,0]
	v_pk_mul_f32 v[38:39], v[38:39], v[160:161] op_sel_hi:[1,0]
	v_pk_mul_f32 v[36:37], v[36:37], v[160:161] op_sel:[0,1] op_sel_hi:[1,1]
	v_pk_mul_f32 v[34:35], v[34:35], v[160:161] op_sel:[0,1] op_sel_hi:[1,1]
	v_pk_mul_f32 v[32:33], v[32:33], v[162:163] op_sel_hi:[1,0]
	v_pk_mul_f32 v[30:31], v[30:31], v[162:163] op_sel_hi:[1,0]
	v_pk_mul_f32 v[28:29], v[28:29], v[162:163] op_sel:[0,1] op_sel_hi:[1,1]
	v_pk_mul_f32 v[26:27], v[26:27], v[162:163] op_sel:[0,1] op_sel_hi:[1,1]
	v_pk_mul_f32 v[24:25], v[24:25], v[164:165] op_sel_hi:[1,0]
	v_pk_mul_f32 v[22:23], v[22:23], v[164:165] op_sel_hi:[1,0]
	v_pk_mul_f32 v[20:21], v[20:21], v[164:165] op_sel:[0,1] op_sel_hi:[1,1]
	v_pk_mul_f32 v[18:19], v[18:19], v[164:165] op_sel:[0,1] op_sel_hi:[1,1]
	v_pk_mul_f32 v[16:17], v[16:17], v[166:167] op_sel_hi:[1,0]
	v_pk_mul_f32 v[14:15], v[14:15], v[166:167] op_sel_hi:[1,0]
	v_pk_mul_f32 v[12:13], v[12:13], v[166:167] op_sel:[0,1] op_sel_hi:[1,1]
	v_pk_mul_f32 v[10:11], v[10:11], v[166:167] op_sel:[0,1] op_sel_hi:[1,1]
	v_pk_mul_f32 v[8:9], v[8:9], v[168:169] op_sel_hi:[1,0]
	v_pk_mul_f32 v[6:7], v[6:7], v[168:169] op_sel_hi:[1,0]
	v_pk_mul_f32 v[4:5], v[4:5], v[168:169] op_sel:[0,1] op_sel_hi:[1,1]
	v_pk_mul_f32 v[2:3], v[2:3], v[168:169] op_sel:[0,1] op_sel_hi:[1,1]
	v_pk_mul_f32 v[48:49], v[48:49], v[170:171] op_sel_hi:[1,0]
	v_pk_mul_f32 v[46:47], v[46:47], v[170:171] op_sel_hi:[1,0]
	v_pk_mul_f32 v[44:45], v[44:45], v[170:171] op_sel:[0,1] op_sel_hi:[1,1]
	v_pk_mul_f32 v[42:43], v[42:43], v[170:171] op_sel:[0,1] op_sel_hi:[1,1]
	v_pk_mul_f32 v[56:57], v[56:57], v[172:173] op_sel_hi:[1,0]
	v_pk_mul_f32 v[54:55], v[54:55], v[172:173] op_sel_hi:[1,0]
	v_pk_mul_f32 v[52:53], v[52:53], v[172:173] op_sel:[0,1] op_sel_hi:[1,1]
	v_pk_mul_f32 v[50:51], v[50:51], v[172:173] op_sel:[0,1] op_sel_hi:[1,1]
	v_pk_mul_f32 v[64:65], v[64:65], v[174:175] op_sel_hi:[1,0]
	v_pk_mul_f32 v[62:63], v[62:63], v[174:175] op_sel_hi:[1,0]
	v_pk_mul_f32 v[60:61], v[60:61], v[174:175] op_sel:[0,1] op_sel_hi:[1,1]
	v_pk_mul_f32 v[58:59], v[58:59], v[174:175] op_sel:[0,1] op_sel_hi:[1,1]

; DI void tr_item(const float* W, int ldw, int k0, int col, const float* gain, bf16* dst_n0, int K, LAS float* scr, int lane) {
;     ...
;     f32x4 v[16];
; #pragma unroll
;     for (int i = 0; i < 16; ++i) { v[i] = (f32x4){0.f, 0.f, 0.f, 0.f}; if (col >= 0) v[i] = *(const f32x4*)(W + (size_t)(k0 + 4 * i + kr) * ldw + col); }
;     if (gain) {
; #pragma unroll
;         for (int i = 0; i < 16; ++i) v[i] *= gain[k0 + 4 * i + kr];
;     }
.LBB0_273:
	s_andn2_saveexec_b64 s[26:27], s[26:27]
	v_or_b32_e32 v0, 0x800, v3
	s_or_b64 exec, exec, s[26:27]
	v_lshlrev_b32_sdwa v66, v228, v2 dst_sel:DWORD dst_unused:UNUSED_PAD src0_sel:DWORD src1_sel:WORD_0
	v_or_b32_e32 v83, v66, v73
	v_lshl_add_u64 v[2:3], v[0:1], 2, s[24:25]
	v_mul_u32_u24_e32 v0, 0x1620, v83
	v_lshl_add_u64 v[58:59], v[0:1], 2, v[2:3]
	v_add_co_u32_e32 v2, vcc, 0x16000, v58
	v_readlane_b32 s26, v253, 14
	s_nop 0
	v_addc_co_u32_e32 v3, vcc, 0, v59, vcc
	v_add_co_u32_e32 v10, vcc, 0x2c000, v58
	global_load_dwordx4 v[6:9], v[58:59], off
	s_nop 0
	global_load_dwordx4 v[2:5], v[2:3], off offset:512
	v_addc_co_u32_e32 v11, vcc, 0, v59, vcc
	v_add_co_u32_e32 v12, vcc, 0x42000, v58
	v_readlane_b32 s27, v253, 15
	s_nop 0
	v_addc_co_u32_e32 v13, vcc, 0, v59, vcc
	v_add_co_u32_e32 v18, vcc, 0x58000, v58
	global_load_dwordx4 v[14:17], v[10:11], off offset:1024
	s_nop 0
	global_load_dwordx4 v[10:13], v[12:13], off offset:1536
	v_addc_co_u32_e32 v19, vcc, 0, v59, vcc
	v_add_co_u32_e32 v20, vcc, 0x6e000, v58
	s_nop 1
	v_addc_co_u32_e32 v21, vcc, 0, v59, vcc
	v_add_co_u32_e32 v26, vcc, 0x84000, v58
	global_load_dwordx4 v[22:25], v[18:19], off offset:2048
	s_nop 0
	global_load_dwordx4 v[18:21], v[20:21], off offset:2560
	v_addc_co_u32_e32 v27, vcc, 0, v59, vcc
	v_add_co_u32_e32 v28, vcc, 0x9a000, v58
	s_nop 1
	v_addc_co_u32_e32 v29, vcc, 0, v59, vcc
	v_add_co_u32_e32 v34, vcc, 0xb1000, v58
	global_load_dwordx4 v[30:33], v[26:27], off offset:3072
	s_nop 0
	global_load_dwordx4 v[26:29], v[28:29], off offset:3584
	v_addc_co_u32_e32 v35, vcc, 0, v59, vcc
	v_add_co_u32_e32 v36, vcc, 0xc7000, v58
	s_nop 1
	v_addc_co_u32_e32 v37, vcc, 0, v59, vcc
	v_add_co_u32_e32 v42, vcc, 0xdd000, v58
	global_load_dwordx4 v[38:41], v[34:35], off
	s_nop 0
	global_load_dwordx4 v[34:37], v[36:37], off offset:512
	v_addc_co_u32_e32 v43, vcc, 0, v59, vcc
	v_add_co_u32_e32 v44, vcc, 0xf3000, v58
	s_nop 1
	v_addc_co_u32_e32 v45, vcc, 0, v59, vcc
	v_add_co_u32_e32 v50, vcc, 0x109000, v58
	global_load_dwordx4 v[46:49], v[42:43], off offset:1024
	s_nop 0
	global_load_dwordx4 v[42:45], v[44:45], off offset:1536
	v_addc_co_u32_e32 v51, vcc, 0, v59, vcc
	v_add_co_u32_e32 v52, vcc, 0x11f000, v58
	s_nop 1
	v_addc_co_u32_e32 v53, vcc, 0, v59, vcc
	v_add_co_u32_e32 v60, vcc, 0x135000, v58
	global_load_dwordx4 v[54:57], v[50:51], off offset:2048
	s_nop 0
	global_load_dwordx4 v[50:53], v[52:53], off offset:2560
	v_addc_co_u32_e32 v61, vcc, 0, v59, vcc
	v_add_co_u32_e32 v58, vcc, 0x14b000, v58
	s_nop 1
	v_addc_co_u32_e32 v59, vcc, 0, v59, vcc
	global_load_dwordx4 v[62:65], v[60:61], off offset:3072
	s_nop 0
	global_load_dwordx4 v[58:61], v[58:59], off offset:3584
	s_andn2_b64 vcc, exec, s[26:27]
	s_cbranch_vccnz .LBB0_277
	v_lshlrev_b32_e32 v83, 2, v83
	global_load_dword v160, v83, s[40:41]
	global_load_dword v161, v83, s[40:41] offset:16
	global_load_dword v162, v83, s[40:41] offset:32
	global_load_dword v163, v83, s[40:41] offset:48
	global_load_dword v164, v83, s[40:41] offset:64
	global_load_dword v165, v83, s[40:41] offset:80
	global_load_dword v166, v83, s[40:41] offset:96
	global_load_dword v167, v83, s[40:41] offset:112
	global_load_dword v168, v83, s[40:41] offset:128
	global_load_dword v169, v83, s[40:41] offset:144
	global_load_dword v170, v83, s[40:41] offset:160
	global_load_dword v171, v83, s[40:41] offset:176
	global_load_dword v172, v83, s[40:41] offset:192
	global_load_dword v173, v83, s[40:41] offset:208
	global_load_dword v174, v83, s[40:41] offset:224
	global_load_dword v175, v83, s[40:41] offset:240
	s_waitcnt vmcnt(0)
	v_pk_mul_f32 v[8:9], v[8:9], v[160:161] op_sel_hi:[1,0]
	v_pk_mul_f32 v[6:7], v[6:7], v[160:161] op_sel_hi:[1,0]
	v_pk_mul_f32 v[4:5], v[4:5], v[160:161] op_sel:[0,1] op_sel_hi:[1,1]
	v_pk_mul_f32 v[2:3], v[2:3], v[160:161] op_sel:[0,1] op_sel_hi:[1,1]
	v_pk_mul_f32 v[16:17], v[16:17], v[162:163] op_sel_hi:[1,0]
	v_pk_mul_f32 v[14:15], v[14:15], v[162:163] op_sel_hi:[1,0]
	v_pk_mul_f32 v[12:13], v[12:13], v[162:163] op_sel:[0,1] op_sel_hi:[1,1]
	v_pk_mul_f32 v[10:11], v[10:11], v[162:163] op_sel:[0,1] op_sel_hi:[1,1]
	v_pk_mul_f32 v[24:25], v[24:25], v[164:165] op_sel_hi:[1,0]
	v_pk_mul_f32 v[22:23], v[22:23], v[164:165] op_sel_hi:[1,0]
	v_pk_mul_f32 v[20:21], v[20:21], v[164:165] op_sel:[0,1] op_sel_hi:[1,1]
	v_pk_mul_f32 v[18:19], v[18:19], v[164:165] op_sel:[0,1] op_sel_hi:[1,1]
	v_pk_mul_f32 v[32:33], v[32:33], v[166:167] op_sel_hi:[1,0]
	v_pk_mul_f32 v[30:31], v[30:31], v[166:167] op_sel_hi:[1,0]
	v_pk_mul_f32 v[28:29], v[28:29], v[166:167] op_sel:[0,1] op_sel_hi:[1,1]
	v_pk_mul_f32 v[26:27], v[26:27], v[166:167] op_sel:[0,1] op_sel_hi:[1,1]
	v_pk_mul_f32 v[40:41], v[40:41], v[168:169] op_sel_hi:[1,0]
	v_pk_mul_f32 v[38:39], v[38:39], v[168:169] op_sel_hi:[1,0]
	v_pk_mul_f32 v[36:37], v[36:37], v[168:169] op_sel:[0,1] op_sel_hi:[1,1]
	v_pk_mul_f32 v[34:35], v[34:35], v[168:169] op_sel:[0,1] op_sel_hi:[1,1]
	v_pk_mul_f32 v[48:49], v[48:49], v[170:171] op_sel_hi:[1,0]
	v_pk_mul_f32 v[46:47], v[46:47], v[170:171] op_sel_hi:[1,0]
	v_pk_mul_f32 v[44:45], v[44:45], v[170:171] op_sel:[0,1] op_sel_hi:[1,1]
	v_pk_mul_f32 v[42:43], v[42:43], v[170:171] op_sel:[0,1] op_sel_hi:[1,1]
	v_pk_mul_f32 v[56:57], v[56:57], v[172:173] op_sel_hi:[1,0]
	v_pk_mul_f32 v[54:55], v[54:55], v[172:173] op_sel_hi:[1,0]
	v_pk_mul_f32 v[52:53], v[52:53], v[172:173] op_sel:[0,1] op_sel_hi:[1,1]
	v_pk_mul_f32 v[50:51], v[50:51], v[172:173] op_sel:[0,1] op_sel_hi:[1,1]
	v_pk_mul_f32 v[64:65], v[64:65], v[174:175] op_sel_hi:[1,0]
	v_pk_mul_f32 v[62:63], v[62:63], v[174:175] op_sel_hi:[1,0]
	v_pk_mul_f32 v[60:61], v[60:61], v[174:175] op_sel:[0,1] op_sel_hi:[1,1]
	v_pk_mul_f32 v[58:59], v[58:59], v[174:175] op_sel:[0,1] op_sel_hi:[1,1]

; DI void tr_item(const float* W, int ldw, int k0, int col, const float* gain, bf16* dst_n0, int K, LAS float* scr, int lane) {
;     ...
;     f32x4 v[16];
; #pragma unroll
;     for (int i = 0; i < 16; ++i) { v[i] = (f32x4){0.f, 0.f, 0.f, 0.f}; if (col >= 0) v[i] = *(const f32x4*)(W + (size_t)(k0 + 4 * i + kr) * ldw + col); }
;     if (gain) {
; #pragma unroll
;         for (int i = 0; i < 16; ++i) v[i] *= gain[k0 + 4 * i + kr];
;     }
.LBB0_326:
	s_or_b64 exec, exec, s[26:27]
	v_readlane_b32 s26, v253, 14
	v_readlane_b32 s27, v253, 15
	s_and_b64 vcc, exec, s[26:27]
	s_cbranch_vccz .LBB0_251
	v_ashrrev_i32_e32 v101, 31, v100
	v_lshl_add_u64 v[2:3], v[100:101], 2, s[40:41]
	global_load_dword v160, v[2:3], off
	global_load_dword v161, v[2:3], off offset:16
	global_load_dword v162, v[2:3], off offset:32
	global_load_dword v163, v[2:3], off offset:48
	global_load_dword v164, v[2:3], off offset:64
	global_load_dword v165, v[2:3], off offset:80
	global_load_dword v166, v[2:3], off offset:96
	global_load_dword v167, v[2:3], off offset:112
	global_load_dword v168, v[2:3], off offset:128
	global_load_dword v169, v[2:3], off offset:144
	global_load_dword v170, v[2:3], off offset:160
	global_load_dword v171, v[2:3], off offset:176
	global_load_dword v172, v[2:3], off offset:192
	global_load_dword v173, v[2:3], off offset:208
	global_load_dword v174, v[2:3], off offset:224
	global_load_dword v175, v[2:3], off offset:240
	s_waitcnt vmcnt(0)
	v_pk_mul_f32 v[6:7], v[6:7], v[160:161] op_sel_hi:[1,0]
	v_pk_mul_f32 v[4:5], v[4:5], v[160:161] op_sel_hi:[1,0]
	v_pk_mul_f32 v[10:11], v[10:11], v[160:161] op_sel:[0,1] op_sel_hi:[1,1]
	v_pk_mul_f32 v[8:9], v[8:9], v[160:161] op_sel:[0,1] op_sel_hi:[1,1]
	v_pk_mul_f32 v[14:15], v[14:15], v[162:163] op_sel_hi:[1,0]
	v_pk_mul_f32 v[12:13], v[12:13], v[162:163] op_sel_hi:[1,0]
	v_pk_mul_f32 v[18:19], v[18:19], v[162:163] op_sel:[0,1] op_sel_hi:[1,1]
	v_pk_mul_f32 v[16:17], v[16:17], v[162:163] op_sel:[0,1] op_sel_hi:[1,1]
	v_pk_mul_f32 v[22:23], v[22:23], v[164:165] op_sel_hi:[1,0]
	v_pk_mul_f32 v[20:21], v[20:21], v[164:165] op_sel_hi:[1,0]
	v_pk_mul_f32 v[26:27], v[26:27], v[164:165] op_sel:[0,1] op_sel_hi:[1,1]
	v_pk_mul_f32 v[24:25], v[24:25], v[164:165] op_sel:[0,1] op_sel_hi:[1,1]
	v_pk_mul_f32 v[30:31], v[30:31], v[166:167] op_sel_hi:[1,0]
	v_pk_mul_f32 v[28:29], v[28:29], v[166:167] op_sel_hi:[1,0]
	v_pk_mul_f32 v[34:35], v[34:35], v[166:167] op_sel:[0,1] op_sel_hi:[1,1]
	v_pk_mul_f32 v[32:33], v[32:33], v[166:167] op_sel:[0,1] op_sel_hi:[1,1]
	v_pk_mul_f32 v[38:39], v[38:39], v[168:169] op_sel_hi:[1,0]
	v_pk_mul_f32 v[36:37], v[36:37], v[168:169] op_sel_hi:[1,0]
	v_pk_mul_f32 v[42:43], v[42:43], v[168:169] op_sel:[0,1] op_sel_hi:[1,1]
	v_pk_mul_f32 v[40:41], v[40:41], v[168:169] op_sel:[0,1] op_sel_hi:[1,1]
	v_pk_mul_f32 v[46:47], v[46:47], v[170:171] op_sel_hi:[1,0]
	v_pk_mul_f32 v[44:45], v[44:45], v[170:171] op_sel_hi:[1,0]
	v_pk_mul_f32 v[50:51], v[50:51], v[170:171] op_sel:[0,1] op_sel_hi:[1,1]
	v_pk_mul_f32 v[48:49], v[48:49], v[170:171] op_sel:[0,1] op_sel_hi:[1,1]
	v_pk_mul_f32 v[54:55], v[54:55], v[172:173] op_sel_hi:[1,0]
	v_pk_mul_f32 v[52:53], v[52:53], v[172:173] op_sel_hi:[1,0]
	v_pk_mul_f32 v[58:59], v[58:59], v[172:173] op_sel:[0,1] op_sel_hi:[1,1]
	v_pk_mul_f32 v[56:57], v[56:57], v[172:173] op_sel:[0,1] op_sel_hi:[1,1]
	v_pk_mul_f32 v[62:63], v[62:63], v[174:175] op_sel_hi:[1,0]
	v_pk_mul_f32 v[60:61], v[60:61], v[174:175] op_sel_hi:[1,0]
	v_pk_mul_f32 v[66:67], v[66:67], v[174:175] op_sel:[0,1] op_sel_hi:[1,1]
	v_pk_mul_f32 v[64:65], v[64:65], v[174:175] op_sel:[0,1] op_sel_hi:[1,1]
	s_branch .LBB0_251

; DI void tr_item(const float* W, int ldw, int k0, int col, const float* gain, bf16* dst_n0, int K, LAS float* scr, int lane) {
;     ...
;     f32x4 v[16];
; #pragma unroll
;     for (int i = 0; i < 16; ++i) { v[i] = (f32x4){0.f, 0.f, 0.f, 0.f}; if (col >= 0) v[i] = *(const f32x4*)(W + (size_t)(k0 + 4 * i + kr) * ldw + col); }
;     if (gain) {
; #pragma unroll
;         for (int i = 0; i < 16; ++i) v[i] *= gain[k0 + 4 * i + kr];
;     }
; DI void convert_weights(const P& p, ldsp lds, int l, int part, int nb, int bi, int wv) {
;     ...
;         if (r < IGU) { const int nb = r % (NGU / 64), kb = r / (NGU / 64); const int n = nb * 64, pp = n >> 8, sg = (n >> 7) & 1, j = n & 127;
;             tr_item((sg ? p.w_up : p.w_gate) + (size_t)l * DM * FF, FF, kb * 64, 128 * pp + j + nl, p.ffn_norm + l * DM, (bf16*)(wl + OWGU) + (size_t)n * DM, DM, scr, lane); continue; } r -= IGU;
.LBB0_342:
	s_andn2_saveexec_b64 s[18:19], s[18:19]
	s_cbranch_execz .LBB0_346
	v_add_u16_e32 v0, 0xf080, v2
	v_mul_u32_u24_e32 v2, 0xba2f, v0
	v_lshrrev_b32_e32 v4, 23, v2
	v_mul_lo_u16_e32 v2, 0xb0, v4
	v_sub_u16_e32 v67, v0, v2
	v_and_b32_e32 v0, 2, v67
	v_cmp_eq_u32_e32 vcc, 0, v0
	v_mov_b32_e32 v0, 0x88
	v_mov_b32_e32 v2, 0x80
	v_readlane_b32 s20, v252, 3
	v_cndmask_b32_e32 v0, v0, v2, vcc
	v_readlane_b32 s21, v252, 4
	v_lshlrev_b16_e32 v66, 6, v4
	v_lshlrev_b32_e32 v4, 5, v67
	v_lshl_add_u64 v[2:3], s[20:21], 0, v[0:1]
	global_load_dwordx2 v[2:3], v[2:3], off
	v_lshlrev_b32_e32 v0, 6, v67
	v_and_b32_e32 v0, 64, v0
	v_and_b32_e32 v4, 0x1f80, v4
	v_or_b32_e32 v81, v73, v66
	v_or3_b32 v0, v4, v0, v71
	v_mul_u32_u24_e32 v5, 0x1600, v81
	v_lshlrev_b32_e32 v0, 2, v0
	s_mov_b32 s9, 0x2c00000
	v_readlane_b32 s20, v253, 12
	v_readlane_b32 s21, v253, 13
	s_waitcnt vmcnt(0)
	v_lshl_add_u64 v[2:3], v[2:3], 0, v[0:1]
	v_lshlrev_b32_e32 v0, 2, v5
	v_lshl_add_u64 v[58:59], v[2:3], 0, v[0:1]
	v_add_co_u32_e32 v2, vcc, s9, v58
	s_mov_b32 s9, 0x2c16000
	s_nop 0
	v_addc_co_u32_e32 v3, vcc, 0, v59, vcc
	v_add_co_u32_e32 v4, vcc, s9, v58
	s_mov_b32 s9, 0x2c2c000
	s_nop 0
	v_addc_co_u32_e32 v5, vcc, 0, v59, vcc
	v_add_co_u32_e32 v6, vcc, s9, v58
	s_mov_b32 s9, 0x2c42000
	s_nop 0
	v_addc_co_u32_e32 v7, vcc, 0, v59, vcc
	v_add_co_u32_e32 v8, vcc, s9, v58
	s_mov_b32 s9, 0x2c58000
	s_nop 0
	v_addc_co_u32_e32 v9, vcc, 0, v59, vcc
	v_add_co_u32_e32 v10, vcc, s9, v58
	s_mov_b32 s9, 0x2c6e000
	s_nop 0
	v_addc_co_u32_e32 v11, vcc, 0, v59, vcc
	v_add_co_u32_e32 v12, vcc, s9, v58
	s_mov_b32 s9, 0x2c84000
	s_nop 0
	v_addc_co_u32_e32 v13, vcc, 0, v59, vcc
	v_add_co_u32_e32 v14, vcc, s9, v58
	s_mov_b32 s9, 0x2c9a000
	s_nop 0
	v_addc_co_u32_e32 v15, vcc, 0, v59, vcc
	v_add_co_u32_e32 v42, vcc, s9, v58
	s_mov_b32 s9, 0x2cb0000
	s_nop 0
	v_addc_co_u32_e32 v43, vcc, 0, v59, vcc
	v_add_co_u32_e32 v44, vcc, s9, v58
	s_mov_b32 s9, 0x2cc6000
	s_nop 0
	v_addc_co_u32_e32 v45, vcc, 0, v59, vcc
	v_add_co_u32_e32 v46, vcc, s9, v58
	s_mov_b32 s9, 0x2cdc000
	s_nop 0
	v_addc_co_u32_e32 v47, vcc, 0, v59, vcc
	v_add_co_u32_e32 v48, vcc, s9, v58
	s_mov_b32 s9, 0x2cf2000
	s_nop 0
	v_addc_co_u32_e32 v49, vcc, 0, v59, vcc
	global_load_dwordx4 v[38:41], v[2:3], off
	global_load_dwordx4 v[34:37], v[4:5], off
	global_load_dwordx4 v[30:33], v[6:7], off
	global_load_dwordx4 v[26:29], v[8:9], off
	global_load_dwordx4 v[22:25], v[10:11], off
	global_load_dwordx4 v[18:21], v[12:13], off
	s_nop 0
	global_load_dwordx4 v[14:17], v[14:15], off
	s_nop 0
	global_load_dwordx4 v[10:13], v[42:43], off
	global_load_dwordx4 v[6:9], v[44:45], off
	global_load_dwordx4 v[2:5], v[46:47], off
	v_add_co_u32_e32 v42, vcc, s9, v58
	s_mov_b32 s9, 0x2d08000
	s_nop 0
	v_addc_co_u32_e32 v43, vcc, 0, v59, vcc
	v_add_co_u32_e32 v50, vcc, s9, v58
	global_load_dwordx4 v[46:49], v[48:49], off
	s_nop 0
	global_load_dwordx4 v[42:45], v[42:43], off
	v_addc_co_u32_e32 v51, vcc, 0, v59, vcc
	v_add_co_u32_e32 v52, vcc, 0x2d1e000, v58
	s_nop 1
	v_addc_co_u32_e32 v53, vcc, 0, v59, vcc
	v_add_co_u32_e32 v60, vcc, 0x2d34000, v58
	global_load_dwordx4 v[54:57], v[50:51], off
	s_nop 0
	global_load_dwordx4 v[50:53], v[52:53], off
	v_addc_co_u32_e32 v61, vcc, 0, v59, vcc
	v_add_co_u32_e32 v58, vcc, 0x2d4a000, v58
	s_nop 1
	v_addc_co_u32_e32 v59, vcc, 0, v59, vcc
	global_load_dwordx4 v[62:65], v[60:61], off
	s_nop 0
	global_load_dwordx4 v[58:61], v[58:59], off
	s_andn2_b64 vcc, exec, s[20:21]
	s_cbranch_vccnz .LBB0_345
	v_readlane_b32 s20, v253, 30
	v_lshlrev_b32_e32 v81, 2, v81
	v_readlane_b32 s21, v253, 31
	s_nop 4
	global_load_dword v160, v81, s[20:21]
	global_load_dword v161, v81, s[20:21] offset:16
	global_load_dword v162, v81, s[20:21] offset:32
	global_load_dword v163, v81, s[20:21] offset:48
	global_load_dword v164, v81, s[20:21] offset:64
	global_load_dword v165, v81, s[20:21] offset:80
	global_load_dword v166, v81, s[20:21] offset:96
	global_load_dword v167, v81, s[20:21] offset:112
	global_load_dword v168, v81, s[20:21] offset:128
	global_load_dword v169, v81, s[20:21] offset:144
	global_load_dword v170, v81, s[20:21] offset:160
	global_load_dword v171, v81, s[20:21] offset:176
	global_load_dword v172, v81, s[20:21] offset:192
	global_load_dword v173, v81, s[20:21] offset:208
	global_load_dword v174, v81, s[20:21] offset:224
	global_load_dword v175, v81, s[20:21] offset:240
	s_waitcnt vmcnt(0)
	v_pk_mul_f32 v[40:41], v[40:41], v[160:161] op_sel_hi:[1,0]
	v_pk_mul_f32 v[38:39], v[38:39], v[160:161] op_sel_hi:[1,0]
	v_pk_mul_f32 v[36:37], v[36:37], v[160:161] op_sel:[0,1] op_sel_hi:[1,1]
	v_pk_mul_f32 v[34:35], v[34:35], v[160:161] op_sel:[0,1] op_sel_hi:[1,1]
	v_pk_mul_f32 v[32:33], v[32:33], v[162:163] op_sel_hi:[1,0]
	v_pk_mul_f32 v[30:31], v[30:31], v[162:163] op_sel_hi:[1,0]
	v_pk_mul_f32 v[28:29], v[28:29], v[162:163] op_sel:[0,1] op_sel_hi:[1,1]
	v_pk_mul_f32 v[26:27], v[26:27], v[162:163] op_sel:[0,1] op_sel_hi:[1,1]
	v_pk_mul_f32 v[24:25], v[24:25], v[164:165] op_sel_hi:[1,0]
	v_pk_mul_f32 v[22:23], v[22:23], v[164:165] op_sel_hi:[1,0]
	v_pk_mul_f32 v[20:21], v[20:21], v[164:165] op_sel:[0,1] op_sel_hi:[1,1]
	v_pk_mul_f32 v[18:19], v[18:19], v[164:165] op_sel:[0,1] op_sel_hi:[1,1]
	v_pk_mul_f32 v[16:17], v[16:17], v[166:167] op_sel_hi:[1,0]
	v_pk_mul_f32 v[14:15], v[14:15], v[166:167] op_sel_hi:[1,0]
	v_pk_mul_f32 v[12:13], v[12:13], v[166:167] op_sel:[0,1] op_sel_hi:[1,1]
	v_pk_mul_f32 v[10:11], v[10:11], v[166:167] op_sel:[0,1] op_sel_hi:[1,1]
	v_pk_mul_f32 v[8:9], v[8:9], v[168:169] op_sel_hi:[1,0]
	v_pk_mul_f32 v[6:7], v[6:7], v[168:169] op_sel_hi:[1,0]
	v_pk_mul_f32 v[4:5], v[4:5], v[168:169] op_sel:[0,1] op_sel_hi:[1,1]
	v_pk_mul_f32 v[2:3], v[2:3], v[168:169] op_sel:[0,1] op_sel_hi:[1,1]
	v_pk_mul_f32 v[48:49], v[48:49], v[170:171] op_sel_hi:[1,0]
	v_pk_mul_f32 v[46:47], v[46:47], v[170:171] op_sel_hi:[1,0]
	v_pk_mul_f32 v[44:45], v[44:45], v[170:171] op_sel:[0,1] op_sel_hi:[1,1]
	v_pk_mul_f32 v[42:43], v[42:43], v[170:171] op_sel:[0,1] op_sel_hi:[1,1]
	v_pk_mul_f32 v[56:57], v[56:57], v[172:173] op_sel_hi:[1,0]
	v_pk_mul_f32 v[54:55], v[54:55], v[172:173] op_sel_hi:[1,0]
	v_pk_mul_f32 v[52:53], v[52:53], v[172:173] op_sel:[0,1] op_sel_hi:[1,1]
	v_pk_mul_f32 v[50:51], v[50:51], v[172:173] op_sel:[0,1] op_sel_hi:[1,1]
	v_pk_mul_f32 v[64:65], v[64:65], v[174:175] op_sel_hi:[1,0]
	v_pk_mul_f32 v[62:63], v[62:63], v[174:175] op_sel_hi:[1,0]
	v_pk_mul_f32 v[60:61], v[60:61], v[174:175] op_sel:[0,1] op_sel_hi:[1,1]
	v_pk_mul_f32 v[58:59], v[58:59], v[174:175] op_sel:[0,1] op_sel_hi:[1,1]

; DI void tr_item(const float* W, int ldw, int k0, int col, const float* gain, bf16* dst_n0, int K, LAS float* scr, int lane) {
;     ...
;     f32x4 v[16];
; #pragma unroll
;     for (int i = 0; i < 16; ++i) { v[i] = (f32x4){0.f, 0.f, 0.f, 0.f}; if (col >= 0) v[i] = *(const f32x4*)(W + (size_t)(k0 + 4 * i + kr) * ldw + col); }
;     if (gain) {
; #pragma unroll
;         for (int i = 0; i < 16; ++i) v[i] *= gain[k0 + 4 * i + kr];
;     }
; DI void convert_weights(const P& p, ldsp lds, int l, int part, int nb, int bi, int wv) {
;     ...
;             tr_item(p.w_in + (size_t)l * DM * INW, INW, kb * 64, srccol_in(0, nb * 64 + nl), p.attn_norm + l * DM, (bf16*)(wl + OW1) + (size_t)nb * 64 * DM, DM, scr, lane); continue; } r -= I1;
.LBB0_357:
	s_andn2_saveexec_b64 s[14:15], s[14:15]
	v_or_b32_e32 v0, 0x800, v3
	s_or_b64 exec, exec, s[14:15]
	v_lshlrev_b32_sdwa v66, v228, v2 dst_sel:DWORD dst_unused:UNUSED_PAD src0_sel:DWORD src1_sel:WORD_0
	v_readlane_b32 s14, v253, 40
	v_or_b32_e32 v81, v66, v73
	v_readlane_b32 s15, v253, 41
	s_nop 1
	v_lshl_add_u64 v[2:3], v[0:1], 2, s[14:15]
	v_mul_u32_u24_e32 v0, 0x1620, v81
	v_lshl_add_u64 v[58:59], v[0:1], 2, v[2:3]
	v_add_co_u32_e32 v2, vcc, 0x16000, v58
	v_readlane_b32 s14, v253, 14
	s_nop 0
	v_addc_co_u32_e32 v3, vcc, 0, v59, vcc
	v_add_co_u32_e32 v10, vcc, 0x2c000, v58
	global_load_dwordx4 v[6:9], v[58:59], off
	s_nop 0
	global_load_dwordx4 v[2:5], v[2:3], off offset:512
	v_addc_co_u32_e32 v11, vcc, 0, v59, vcc
	v_add_co_u32_e32 v12, vcc, 0x42000, v58
	v_readlane_b32 s15, v253, 15
	s_nop 0
	v_addc_co_u32_e32 v13, vcc, 0, v59, vcc
	v_add_co_u32_e32 v18, vcc, 0x58000, v58
	global_load_dwordx4 v[14:17], v[10:11], off offset:1024
	s_nop 0
	global_load_dwordx4 v[10:13], v[12:13], off offset:1536
	v_addc_co_u32_e32 v19, vcc, 0, v59, vcc
	v_add_co_u32_e32 v20, vcc, 0x6e000, v58
	s_nop 1
	v_addc_co_u32_e32 v21, vcc, 0, v59, vcc
	v_add_co_u32_e32 v26, vcc, 0x84000, v58
	global_load_dwordx4 v[22:25], v[18:19], off offset:2048
	s_nop 0
	global_load_dwordx4 v[18:21], v[20:21], off offset:2560
	v_addc_co_u32_e32 v27, vcc, 0, v59, vcc
	v_add_co_u32_e32 v28, vcc, 0x9a000, v58
	s_nop 1
	v_addc_co_u32_e32 v29, vcc, 0, v59, vcc
	v_add_co_u32_e32 v34, vcc, 0xb1000, v58
	global_load_dwordx4 v[30:33], v[26:27], off offset:3072
	s_nop 0
	global_load_dwordx4 v[26:29], v[28:29], off offset:3584
	v_addc_co_u32_e32 v35, vcc, 0, v59, vcc
	v_add_co_u32_e32 v36, vcc, 0xc7000, v58
	s_nop 1
	v_addc_co_u32_e32 v37, vcc, 0, v59, vcc
	v_add_co_u32_e32 v42, vcc, 0xdd000, v58
	global_load_dwordx4 v[38:41], v[34:35], off
	s_nop 0
	global_load_dwordx4 v[34:37], v[36:37], off offset:512
	v_addc_co_u32_e32 v43, vcc, 0, v59, vcc
	v_add_co_u32_e32 v44, vcc, 0xf3000, v58
	s_nop 1
	v_addc_co_u32_e32 v45, vcc, 0, v59, vcc
	v_add_co_u32_e32 v50, vcc, 0x109000, v58
	global_load_dwordx4 v[46:49], v[42:43], off offset:1024
	s_nop 0
	global_load_dwordx4 v[42:45], v[44:45], off offset:1536
	v_addc_co_u32_e32 v51, vcc, 0, v59, vcc
	v_add_co_u32_e32 v52, vcc, 0x11f000, v58
	s_nop 1
	v_addc_co_u32_e32 v53, vcc, 0, v59, vcc
	v_add_co_u32_e32 v60, vcc, 0x135000, v58
	global_load_dwordx4 v[54:57], v[50:51], off offset:2048
	s_nop 0
	global_load_dwordx4 v[50:53], v[52:53], off offset:2560
	v_addc_co_u32_e32 v61, vcc, 0, v59, vcc
	v_add_co_u32_e32 v58, vcc, 0x14b000, v58
	s_nop 1
	v_addc_co_u32_e32 v59, vcc, 0, v59, vcc
	global_load_dwordx4 v[62:65], v[60:61], off offset:3072
	s_nop 0
	global_load_dwordx4 v[58:61], v[58:59], off offset:3584
	s_andn2_b64 vcc, exec, s[14:15]
	s_cbranch_vccnz .LBB0_361
	v_readlane_b32 s14, v253, 60
	v_lshlrev_b32_e32 v81, 2, v81
	v_readlane_b32 s15, v253, 61
	s_nop 4
	global_load_dword v160, v81, s[14:15]
	global_load_dword v161, v81, s[14:15] offset:16
	global_load_dword v162, v81, s[14:15] offset:32
	global_load_dword v163, v81, s[14:15] offset:48
	global_load_dword v164, v81, s[14:15] offset:64
	global_load_dword v165, v81, s[14:15] offset:80
	global_load_dword v166, v81, s[14:15] offset:96
	global_load_dword v167, v81, s[14:15] offset:112
	global_load_dword v168, v81, s[14:15] offset:128
	global_load_dword v169, v81, s[14:15] offset:144
	global_load_dword v170, v81, s[14:15] offset:160
	global_load_dword v171, v81, s[14:15] offset:176
	global_load_dword v172, v81, s[14:15] offset:192
	global_load_dword v173, v81, s[14:15] offset:208
	global_load_dword v174, v81, s[14:15] offset:224
	global_load_dword v175, v81, s[14:15] offset:240
	s_waitcnt vmcnt(0)
	v_pk_mul_f32 v[8:9], v[8:9], v[160:161] op_sel_hi:[1,0]
	v_pk_mul_f32 v[6:7], v[6:7], v[160:161] op_sel_hi:[1,0]
	v_pk_mul_f32 v[4:5], v[4:5], v[160:161] op_sel:[0,1] op_sel_hi:[1,1]
	v_pk_mul_f32 v[2:3], v[2:3], v[160:161] op_sel:[0,1] op_sel_hi:[1,1]
	v_pk_mul_f32 v[16:17], v[16:17], v[162:163] op_sel_hi:[1,0]
	v_pk_mul_f32 v[14:15], v[14:15], v[162:163] op_sel_hi:[1,0]
	v_pk_mul_f32 v[12:13], v[12:13], v[162:163] op_sel:[0,1] op_sel_hi:[1,1]
	v_pk_mul_f32 v[10:11], v[10:11], v[162:163] op_sel:[0,1] op_sel_hi:[1,1]
	v_pk_mul_f32 v[24:25], v[24:25], v[164:165] op_sel_hi:[1,0]
	v_pk_mul_f32 v[22:23], v[22:23], v[164:165] op_sel_hi:[1,0]
	v_pk_mul_f32 v[20:21], v[20:21], v[164:165] op_sel:[0,1] op_sel_hi:[1,1]
	v_pk_mul_f32 v[18:19], v[18:19], v[164:165] op_sel:[0,1] op_sel_hi:[1,1]
	v_pk_mul_f32 v[32:33], v[32:33], v[166:167] op_sel_hi:[1,0]
	v_pk_mul_f32 v[30:31], v[30:31], v[166:167] op_sel_hi:[1,0]
	v_pk_mul_f32 v[28:29], v[28:29], v[166:167] op_sel:[0,1] op_sel_hi:[1,1]
	v_pk_mul_f32 v[26:27], v[26:27], v[166:167] op_sel:[0,1] op_sel_hi:[1,1]
	v_pk_mul_f32 v[40:41], v[40:41], v[168:169] op_sel_hi:[1,0]
	v_pk_mul_f32 v[38:39], v[38:39], v[168:169] op_sel_hi:[1,0]
	v_pk_mul_f32 v[36:37], v[36:37], v[168:169] op_sel:[0,1] op_sel_hi:[1,1]
	v_pk_mul_f32 v[34:35], v[34:35], v[168:169] op_sel:[0,1] op_sel_hi:[1,1]
	v_pk_mul_f32 v[48:49], v[48:49], v[170:171] op_sel_hi:[1,0]
	v_pk_mul_f32 v[46:47], v[46:47], v[170:171] op_sel_hi:[1,0]
	v_pk_mul_f32 v[44:45], v[44:45], v[170:171] op_sel:[0,1] op_sel_hi:[1,1]
	v_pk_mul_f32 v[42:43], v[42:43], v[170:171] op_sel:[0,1] op_sel_hi:[1,1]
	v_pk_mul_f32 v[56:57], v[56:57], v[172:173] op_sel_hi:[1,0]
	v_pk_mul_f32 v[54:55], v[54:55], v[172:173] op_sel_hi:[1,0]
	v_pk_mul_f32 v[52:53], v[52:53], v[172:173] op_sel:[0,1] op_sel_hi:[1,1]
	v_pk_mul_f32 v[50:51], v[50:51], v[172:173] op_sel:[0,1] op_sel_hi:[1,1]
	v_pk_mul_f32 v[64:65], v[64:65], v[174:175] op_sel_hi:[1,0]
	v_pk_mul_f32 v[62:63], v[62:63], v[174:175] op_sel_hi:[1,0]
	v_pk_mul_f32 v[60:61], v[60:61], v[174:175] op_sel:[0,1] op_sel_hi:[1,1]
	v_pk_mul_f32 v[58:59], v[58:59], v[174:175] op_sel:[0,1] op_sel_hi:[1,1]

; DI void tr_item(const float* W, int ldw, int k0, int col, const float* gain, bf16* dst_n0, int K, LAS float* scr, int lane) {
;     ...
;     f32x4 v[16];
; #pragma unroll
;     for (int i = 0; i < 16; ++i) { v[i] = (f32x4){0.f, 0.f, 0.f, 0.f}; if (col >= 0) v[i] = *(const f32x4*)(W + (size_t)(k0 + 4 * i + kr) * ldw + col); }
;     if (gain) {
; #pragma unroll
;         for (int i = 0; i < 16; ++i) v[i] *= gain[k0 + 4 * i + kr];
;     }
.LBB0_410:
	s_or_b64 exec, exec, s[12:13]
	v_readlane_b32 s12, v253, 14
	v_readlane_b32 s13, v253, 15
	s_and_b64 vcc, exec, s[12:13]
	s_cbranch_vccz .LBB0_331
	v_readlane_b32 s12, v253, 60
	v_ashrrev_i32_e32 v117, 31, v116
	v_readlane_b32 s13, v253, 61
	s_nop 1
	v_lshl_add_u64 v[2:3], v[116:117], 2, s[12:13]
	global_load_dword v160, v[2:3], off
	global_load_dword v161, v[2:3], off offset:16
	global_load_dword v162, v[2:3], off offset:32
	global_load_dword v163, v[2:3], off offset:48
	global_load_dword v164, v[2:3], off offset:64
	global_load_dword v165, v[2:3], off offset:80
	global_load_dword v166, v[2:3], off offset:96
	global_load_dword v167, v[2:3], off offset:112
	global_load_dword v168, v[2:3], off offset:128
	global_load_dword v169, v[2:3], off offset:144
	global_load_dword v170, v[2:3], off offset:160
	global_load_dword v171, v[2:3], off offset:176
	global_load_dword v172, v[2:3], off offset:192
	global_load_dword v173, v[2:3], off offset:208
	global_load_dword v174, v[2:3], off offset:224
	global_load_dword v175, v[2:3], off offset:240
	s_waitcnt vmcnt(0)
	v_pk_mul_f32 v[6:7], v[6:7], v[160:161] op_sel_hi:[1,0]
	v_pk_mul_f32 v[4:5], v[4:5], v[160:161] op_sel_hi:[1,0]
	v_pk_mul_f32 v[10:11], v[10:11], v[160:161] op_sel:[0,1] op_sel_hi:[1,1]
	v_pk_mul_f32 v[8:9], v[8:9], v[160:161] op_sel:[0,1] op_sel_hi:[1,1]
	v_pk_mul_f32 v[14:15], v[14:15], v[162:163] op_sel_hi:[1,0]
	v_pk_mul_f32 v[12:13], v[12:13], v[162:163] op_sel_hi:[1,0]
	v_pk_mul_f32 v[18:19], v[18:19], v[162:163] op_sel:[0,1] op_sel_hi:[1,1]
	v_pk_mul_f32 v[16:17], v[16:17], v[162:163] op_sel:[0,1] op_sel_hi:[1,1]
	v_pk_mul_f32 v[22:23], v[22:23], v[164:165] op_sel_hi:[1,0]
	v_pk_mul_f32 v[20:21], v[20:21], v[164:165] op_sel_hi:[1,0]
	v_pk_mul_f32 v[26:27], v[26:27], v[164:165] op_sel:[0,1] op_sel_hi:[1,1]
	v_pk_mul_f32 v[24:25], v[24:25], v[164:165] op_sel:[0,1] op_sel_hi:[1,1]
	v_pk_mul_f32 v[30:31], v[30:31], v[166:167] op_sel_hi:[1,0]
	v_pk_mul_f32 v[28:29], v[28:29], v[166:167] op_sel_hi:[1,0]
	v_pk_mul_f32 v[34:35], v[34:35], v[166:167] op_sel:[0,1] op_sel_hi:[1,1]
	v_pk_mul_f32 v[32:33], v[32:33], v[166:167] op_sel:[0,1] op_sel_hi:[1,1]
	v_pk_mul_f32 v[38:39], v[38:39], v[168:169] op_sel_hi:[1,0]
	v_pk_mul_f32 v[36:37], v[36:37], v[168:169] op_sel_hi:[1,0]
	v_pk_mul_f32 v[42:43], v[42:43], v[168:169] op_sel:[0,1] op_sel_hi:[1,1]
	v_pk_mul_f32 v[40:41], v[40:41], v[168:169] op_sel:[0,1] op_sel_hi:[1,1]
	v_pk_mul_f32 v[46:47], v[46:47], v[170:171] op_sel_hi:[1,0]
	v_pk_mul_f32 v[44:45], v[44:45], v[170:171] op_sel_hi:[1,0]
	v_pk_mul_f32 v[50:51], v[50:51], v[170:171] op_sel:[0,1] op_sel_hi:[1,1]
	v_pk_mul_f32 v[48:49], v[48:49], v[170:171] op_sel:[0,1] op_sel_hi:[1,1]
	v_pk_mul_f32 v[54:55], v[54:55], v[172:173] op_sel_hi:[1,0]
	v_pk_mul_f32 v[52:53], v[52:53], v[172:173] op_sel_hi:[1,0]
	v_pk_mul_f32 v[58:59], v[58:59], v[172:173] op_sel:[0,1] op_sel_hi:[1,1]
	v_pk_mul_f32 v[56:57], v[56:57], v[172:173] op_sel:[0,1] op_sel_hi:[1,1]
	v_pk_mul_f32 v[62:63], v[62:63], v[174:175] op_sel_hi:[1,0]
	v_pk_mul_f32 v[60:61], v[60:61], v[174:175] op_sel_hi:[1,0]
	v_pk_mul_f32 v[66:67], v[66:67], v[174:175] op_sel:[0,1] op_sel_hi:[1,1]
	v_pk_mul_f32 v[64:65], v[64:65], v[174:175] op_sel:[0,1] op_sel_hi:[1,1]
	s_branch .LBB0_331

; DI int tid_of(int wv) { int ln; asm volatile("v_mbcnt_lo_u32_b32 %0, -1, 0\n\tv_mbcnt_hi_u32_b32 %0, -1, %0" : "=v"(ln)); return wv * 64 + ln; }
; DI float shx(float v, int m, int lane) { return __builtin_bit_cast(float, __builtin_amdgcn_ds_bpermute((lane ^ m) << 2, __builtin_bit_cast(int, v))); }
; DI void load_q(bf16x8 (&q)[8], const bf16* qrow, int h, const float* gain, int lane) {
;     float ss = 0.f;
; #pragma unroll
;     for (int s = 0; s < 8; ++s) { const u32x4 raw = *(const u32x4*)(qrow + 16 * s + 8 * h);
; #pragma unroll
;         for (int j = 0; j < 4; ++j) { const float a = __builtin_bit_cast(float, raw[j] << 16), b = __builtin_bit_cast(float, raw[j] & 0xffff0000u); ss += a * a + b * b; } }
;     ss += shx(ss, 32, lane);
; DI void fox_unit(const P& p, ldsp lds, int u, int l, int wv) {
;     const int tid = tid_of(wv), lane = tid & 63, w = tid >> 6, r32 = lane & 31, h = lane >> 5;
;     const int qb = 31 - (u >> 4), bh = u & 15, b = bh >> 3, hd = bh & 7;
;     const bf16* heads = (const bf16*)(p.ws + WS_HEADS); const bf16* VT = (const bf16*)(p.ws + WS_VT);
;     const int t = qb * 256 + w * 32 + r32;
;     bf16x8 q[8]; load_q(q, heads + ((size_t)hd * M + b * T + t) * HD, h, p.fqn + l * HD, lane);
; __global__ void __launch_bounds__(NTHR, 2) hybrid_fwd(P p) {
;     ...
;                 if (tid == 0) *qslot = atomicAdd(qctr, 1u);
;                 __syncthreads();
;                 const int v = (int)*qslot;
;                 __syncthreads();
;                 if (v >= 1024) break;
;                 if (v < 512) { const int gg = v < 256 ? 1 : 0, idx = v & 255; if (PH(8)) nsa_unit(p, lds, (idx >> 1) * 4 + ((idx & 1) * 2 + gg), l, wv); }
;                 else { if (PH(7)) fox_unit(p, lds, v - 512, l, wv); }
.LBB0_522:
	s_or_b64 exec, exec, s[2:3]
	v_mov_b32_e32 v0, s29
	s_waitcnt lgkmcnt(0)
	s_barrier
	ds_read_b32 v0, v0
	s_movk_i32 s0, 0x3ff
	s_mov_b64 s[2:3], -1
	s_waitcnt lgkmcnt(0)
	s_barrier
	v_cmp_lt_i32_e32 vcc, s0, v0
	v_readfirstlane_b32 s30, v0
	s_cbranch_vccnz .LBB0_519
	s_cmpk_gt_i32 s30, 0x1ff
	s_cbranch_scc0 .LBB0_588
	s_add_i32 s0, s30, 0xfffffe00
	v_readlane_b32 s1, v252, 5
	v_mbcnt_lo_u32_b32 v114, -1, 0
	v_mbcnt_hi_u32_b32 v114, -1, v114
	s_lshr_b32 s0, s0, 4
	s_xor_b32 s6, s0, 31
	v_add_u32_e32 v33, s1, v114
	v_ashrrev_i32_e32 v0, 1, v33
	s_lshl_b32 s4, s6, 8
	v_and_b32_e32 v0, 0xffffffe0, v0
	v_and_b32_e32 v115, 31, v114
	s_bfe_u32 s7, s30, 0x10003
	s_and_b32 s0, s30, 7
	v_add_u32_e32 v0, s4, v0
	v_or_b32_e32 v196, v0, v115
	s_lshl_b32 s3, s0, 14
	s_lshl_b32 s1, s7, 13
	s_or_b32 s16, s3, s1
	v_ashrrev_i32_e32 v197, 31, v196
	v_lshl_add_u64 v[2:3], s[16:17], 0, v[196:197]
	v_readlane_b32 s8, v253, 10
	v_bfe_u32 v199, v114, 5, 1
	v_lshlrev_b64 v[2:3], 8, v[2:3]
	v_readlane_b32 s9, v253, 11
	v_lshlrev_b32_e32 v0, 4, v199
	v_and_b32_e32 v208, 63, v114
	v_lshl_add_u64 v[2:3], s[8:9], 0, v[2:3]
	v_lshl_add_u64 v[2:3], v[2:3], 0, v[0:1]
	global_load_dwordx4 v[4:7], v[2:3], off
	global_load_dwordx4 v[136:139], v[2:3], off offset:32
	global_load_dwordx4 v[140:143], v[2:3], off offset:64
	global_load_dwordx4 v[144:147], v[2:3], off offset:96
	global_load_dwordx4 v[148:151], v[2:3], off offset:128
	global_load_dwordx4 v[152:155], v[2:3], off offset:160
	global_load_dwordx4 v[156:159], v[2:3], off offset:192
	global_load_dwordx4 v[160:163], v[2:3], off offset:224
	v_readlane_b32 s8, v255, 9
	v_readlane_b32 s9, v255, 10
	v_lshlrev_b32_e32 v14, 2, v208
	v_xor_b32_e32 v197, 0x80, v14
	s_and_b32 s2, s30, 15
	s_lshl_b32 s14, s2, 15
	v_readlane_b32 s2, v254, 0
	s_add_u32 s2, s2, s14
	v_readlane_b32 s3, v254, 1
	s_mov_b32 s5, s17
	s_addc_u32 s3, s3, 0
	s_mov_b64 s[10:11], 0
	s_waitcnt vmcnt(7)
	v_lshlrev_b32_e32 v8, 16, v4
	v_and_b32_e32 v4, 0xffff0000, v4
	v_mul_f32_e32 v4, v4, v4
	v_fmac_f32_e32 v4, v8, v8
	v_lshlrev_b32_e32 v8, 16, v5
	v_and_b32_e32 v5, 0xffff0000, v5
	v_mul_f32_e32 v5, v5, v5
	v_fmac_f32_e32 v5, v8, v8
	v_add_f32_e32 v4, v4, v5
	v_lshlrev_b32_e32 v5, 16, v6
	v_and_b32_e32 v6, 0xffff0000, v6
	v_mul_f32_e32 v6, v6, v6
	v_fmac_f32_e32 v6, v5, v5
	v_add_f32_e32 v4, v6, v4
	v_and_b32_e32 v6, 0xffff0000, v7
	v_lshlrev_b32_e32 v5, 16, v7
	v_mul_f32_e32 v6, v6, v6
	v_fmac_f32_e32 v6, v5, v5
	v_add_f32_e32 v8, v6, v4
	s_waitcnt vmcnt(6)
	v_mov_b32_e32 v4, v136
	v_mov_b32_e32 v5, v137
	v_mov_b32_e32 v6, v138
	v_mov_b32_e32 v7, v139
	v_lshlrev_b32_e32 v9, 16, v4
	v_and_b32_e32 v4, 0xffff0000, v4
	v_mul_f32_e32 v4, v4, v4
	v_fmac_f32_e32 v4, v9, v9
	v_add_f32_e32 v4, v4, v8
	v_lshlrev_b32_e32 v8, 16, v5
	v_and_b32_e32 v5, 0xffff0000, v5
	v_mul_f32_e32 v5, v5, v5
	v_fmac_f32_e32 v5, v8, v8
	v_add_f32_e32 v4, v5, v4
	v_lshlrev_b32_e32 v5, 16, v6
	v_and_b32_e32 v6, 0xffff0000, v6
	v_mul_f32_e32 v6, v6, v6
	v_fmac_f32_e32 v6, v5, v5
	v_add_f32_e32 v4, v6, v4
	v_and_b32_e32 v6, 0xffff0000, v7
	v_lshlrev_b32_e32 v5, 16, v7
	v_mul_f32_e32 v6, v6, v6
	v_fmac_f32_e32 v6, v5, v5
	v_add_f32_e32 v8, v6, v4
	s_waitcnt vmcnt(5)
	v_mov_b32_e32 v4, v140
	v_mov_b32_e32 v5, v141
	v_mov_b32_e32 v6, v142
	v_mov_b32_e32 v7, v143
	v_lshlrev_b32_e32 v9, 16, v4
	v_and_b32_e32 v4, 0xffff0000, v4
	v_mul_f32_e32 v4, v4, v4
	v_fmac_f32_e32 v4, v9, v9
	v_add_f32_e32 v4, v4, v8
	v_lshlrev_b32_e32 v8, 16, v5
	v_and_b32_e32 v5, 0xffff0000, v5
	v_mul_f32_e32 v5, v5, v5
	v_fmac_f32_e32 v5, v8, v8
	v_add_f32_e32 v4, v5, v4
	v_lshlrev_b32_e32 v5, 16, v6
	v_and_b32_e32 v6, 0xffff0000, v6
	v_mul_f32_e32 v6, v6, v6
	v_fmac_f32_e32 v6, v5, v5
	v_add_f32_e32 v4, v6, v4
	v_and_b32_e32 v6, 0xffff0000, v7
	v_lshlrev_b32_e32 v5, 16, v7
	v_mul_f32_e32 v6, v6, v6
	v_fmac_f32_e32 v6, v5, v5
	v_add_f32_e32 v8, v6, v4
	s_waitcnt vmcnt(4)
	v_mov_b32_e32 v4, v144
	v_mov_b32_e32 v5, v145
	v_mov_b32_e32 v6, v146
	v_mov_b32_e32 v7, v147
	v_lshlrev_b32_e32 v9, 16, v4
	v_and_b32_e32 v4, 0xffff0000, v4
	v_mul_f32_e32 v4, v4, v4
	v_fmac_f32_e32 v4, v9, v9
	v_add_f32_e32 v4, v4, v8
	v_lshlrev_b32_e32 v8, 16, v5
	v_and_b32_e32 v5, 0xffff0000, v5
	v_mul_f32_e32 v5, v5, v5
	v_fmac_f32_e32 v5, v8, v8
	v_add_f32_e32 v4, v5, v4
	v_lshlrev_b32_e32 v5, 16, v6
	v_and_b32_e32 v6, 0xffff0000, v6
	v_mul_f32_e32 v6, v6, v6
	v_fmac_f32_e32 v6, v5, v5
	v_add_f32_e32 v4, v6, v4
	v_and_b32_e32 v6, 0xffff0000, v7
	v_lshlrev_b32_e32 v5, 16, v7
	v_mul_f32_e32 v6, v6, v6
	v_fmac_f32_e32 v6, v5, v5
	v_add_f32_e32 v8, v6, v4
	s_waitcnt vmcnt(3)
	v_mov_b32_e32 v4, v148
	v_mov_b32_e32 v5, v149
	v_mov_b32_e32 v6, v150
	v_mov_b32_e32 v7, v151
	v_lshlrev_b32_e32 v9, 16, v4
	v_and_b32_e32 v4, 0xffff0000, v4
	v_mul_f32_e32 v4, v4, v4
	v_fmac_f32_e32 v4, v9, v9
	v_add_f32_e32 v4, v4, v8
	v_lshlrev_b32_e32 v8, 16, v5
	v_and_b32_e32 v5, 0xffff0000, v5
	v_mul_f32_e32 v5, v5, v5
	v_fmac_f32_e32 v5, v8, v8
	v_add_f32_e32 v4, v5, v4
	v_lshlrev_b32_e32 v5, 16, v6
	v_and_b32_e32 v6, 0xffff0000, v6
	v_mul_f32_e32 v6, v6, v6
	v_fmac_f32_e32 v6, v5, v5
	v_add_f32_e32 v4, v6, v4
	v_and_b32_e32 v6, 0xffff0000, v7
	v_lshlrev_b32_e32 v5, 16, v7
	v_mul_f32_e32 v6, v6, v6
	v_fmac_f32_e32 v6, v5, v5
	v_add_f32_e32 v8, v6, v4
	s_waitcnt vmcnt(2)
	v_mov_b32_e32 v4, v152
	v_mov_b32_e32 v5, v153
	v_mov_b32_e32 v6, v154
	v_mov_b32_e32 v7, v155
	v_lshlrev_b32_e32 v9, 16, v4
	v_and_b32_e32 v4, 0xffff0000, v4
	v_mul_f32_e32 v4, v4, v4
	v_fmac_f32_e32 v4, v9, v9
	v_add_f32_e32 v4, v4, v8
	v_lshlrev_b32_e32 v8, 16, v5
	v_and_b32_e32 v5, 0xffff0000, v5
	v_mul_f32_e32 v5, v5, v5
	v_fmac_f32_e32 v5, v8, v8
	v_add_f32_e32 v8, v5, v4
	v_lshlrev_b32_e32 v5, 16, v7
	v_lshlrev_b32_e32 v4, 16, v6
	v_and_b32_e32 v7, 0xffff0000, v7
	v_and_b32_e32 v6, 0xffff0000, v6
	v_pk_mul_f32 v[6:7], v[6:7], v[6:7]
	s_nop 0
	v_pk_fma_f32 v[4:5], v[4:5], v[4:5], v[6:7]
	s_nop 0
	v_add_f32_e32 v4, v4, v8
	v_add_f32_e32 v10, v5, v4
	s_waitcnt vmcnt(1)
; DI float shx(float v, int m, int lane) { return __builtin_bit_cast(float, __builtin_amdgcn_ds_bpermute((lane ^ m) << 2, __builtin_bit_cast(int, v))); }
; DI void load_q(bf16x8 (&q)[8], const bf16* qrow, int h, const float* gain, int lane) {
;     ...
;     for (int s = 0; s < 8; ++s) { const u32x4 raw = *(const u32x4*)(qrow + 16 * s + 8 * h);
; #pragma unroll
;         for (int j = 0; j < 4; ++j) { const float a = __builtin_bit_cast(float, raw[j] << 16), b = __builtin_bit_cast(float, raw[j] & 0xffff0000u); ss += a * a + b * b; } }
;     ss += shx(ss, 32, lane);
;     const float rs = rsqrtf(ss * (1.0f / HD) + EPS) * C2;
;     asm volatile("" ::: "memory");
; #pragma unroll
;     for (int s = 0; s < 8; ++s) {
;         const u32x4 raw = *(const u32x4*)(qrow + 16 * s + 8 * h);
;         const f32x4 g0 = *(const f32x4*)(gain + 16 * s + 8 * h), g1 = *(const f32x4*)(gain + 16 * s + 8 * h + 4);
; DI void fox_unit(const P& p, ldsp lds, int u, int l, int wv) {
;     ...
;     { const float* fq = p.fqn + l * HD; const float* fk = p.fkn + l * HD;
;       float gq = fmaxf(fabsf(fq[lane]), fabsf(fq[lane + 64])), gk = fmaxf(fabsf(fk[lane]), fabsf(fk[lane + 64]));
; #pragma unroll
;       for (int o2 = 1; o2 < 64; o2 <<= 1) { gq = fmaxf(gq, shx(gq, o2, lane)); gk = fmaxf(gk, shx(gk, o2, lane)); }
;       const float BQK = 1.02f * C2 * 128.0f * gq * gk;
;       c.bqk = BQK; c.xsel = false;
;       const float thr = c.cumb[qb * 256] - 2.0f * BQK - 32.0f;
;       const int nt = 4 * qb + 4;
;       const bool skip0 = (lane < nt) && (c.cumb[lane * 64 + 63] < thr);
;       const bool skip1 = (lane + 64 < nt) && (c.cumb[(lane + 64) * 64 + 63] < thr);
	v_mov_b32_e32 v4, v156
	v_mov_b32_e32 v5, v157
	v_mov_b32_e32 v6, v158
	v_mov_b32_e32 v7, v159
	v_lshlrev_b32_e32 v9, 16, v5
	v_lshlrev_b32_e32 v8, 16, v4
	v_and_b32_e32 v5, 0xffff0000, v5
	v_and_b32_e32 v4, 0xffff0000, v4
	v_pk_mul_f32 v[4:5], v[4:5], v[4:5]
	s_nop 0
	v_pk_fma_f32 v[4:5], v[8:9], v[8:9], v[4:5]
	s_nop 0
	v_add_f32_e32 v4, v4, v10
	v_add_f32_e32 v8, v5, v4
	v_lshlrev_b32_e32 v5, 16, v7
	v_lshlrev_b32_e32 v4, 16, v6
	v_and_b32_e32 v7, 0xffff0000, v7
	v_and_b32_e32 v6, 0xffff0000, v6
	v_pk_mul_f32 v[6:7], v[6:7], v[6:7]
	s_nop 0
	v_pk_fma_f32 v[4:5], v[4:5], v[4:5], v[6:7]
	s_nop 0
	v_add_f32_e32 v4, v4, v8
	v_add_f32_e32 v10, v5, v4
	s_waitcnt vmcnt(0)
	v_mov_b32_e32 v4, v160
	v_mov_b32_e32 v5, v161
	v_mov_b32_e32 v6, v162
	v_mov_b32_e32 v7, v163
	global_load_dwordx4 v[136:139], v[2:3], off
	s_waitcnt vmcnt(1)
	v_lshlrev_b32_e32 v9, 16, v5
	v_lshlrev_b32_e32 v8, 16, v4
	v_and_b32_e32 v5, 0xffff0000, v5
	v_and_b32_e32 v4, 0xffff0000, v4
	v_pk_mul_f32 v[4:5], v[4:5], v[4:5]
	s_nop 0
	v_pk_fma_f32 v[4:5], v[8:9], v[8:9], v[4:5]
	s_nop 0
	v_add_f32_e32 v4, v4, v10
	v_add_f32_e32 v8, v5, v4
	v_lshlrev_b32_e32 v5, 16, v7
	v_lshlrev_b32_e32 v4, 16, v6
	v_and_b32_e32 v7, 0xffff0000, v7
	v_and_b32_e32 v6, 0xffff0000, v6
	v_pk_mul_f32 v[6:7], v[6:7], v[6:7]
	v_and_b32_e32 v10, 32, v114
	v_pk_fma_f32 v[4:5], v[4:5], v[4:5], v[6:7]
	s_nop 0
	v_add_f32_e32 v4, v4, v8
	v_add_f32_e32 v201, v5, v4
	global_load_dwordx4 v[180:183], v10, s[8:9] offset:16
	global_load_dwordx4 v[184:187], v10, s[8:9]
	global_load_dwordx4 v[140:143], v[2:3], off offset:32
	global_load_dwordx4 v[172:175], v10, s[8:9] offset:80
	global_load_dwordx4 v[176:179], v10, s[8:9] offset:64
	global_load_dwordx4 v[144:147], v[2:3], off offset:64
	global_load_dwordx4 v[164:167], v10, s[8:9] offset:144
	global_load_dwordx4 v[168:171], v10, s[8:9] offset:128
	global_load_dwordx4 v[148:151], v[2:3], off offset:96
	global_load_dwordx4 v[156:159], v10, s[8:9] offset:208
	global_load_dwordx4 v[160:163], v10, s[8:9] offset:192
	global_load_dwordx4 v[110:113], v[2:3], off offset:128
	global_load_dwordx4 v[106:109], v10, s[8:9] offset:272
	global_load_dwordx4 v[152:155], v10, s[8:9] offset:256
	global_load_dwordx4 v[98:101], v[2:3], off offset:160
	global_load_dwordx4 v[94:97], v10, s[8:9] offset:336
	global_load_dwordx4 v[102:105], v10, s[8:9] offset:320
	global_load_dwordx4 v[86:89], v[2:3], off offset:192
	global_load_dwordx4 v[82:85], v10, s[8:9] offset:400
	global_load_dwordx4 v[90:93], v10, s[8:9] offset:384
	global_load_dwordx4 v[6:9], v[2:3], off offset:224
	s_nop 0
	global_load_dwordx4 v[2:5], v10, s[8:9] offset:464
	s_nop 0
	global_load_dwordx4 v[10:13], v10, s[8:9] offset:448
	s_nop 0
	global_load_dword v15, v14, s[8:9]
	global_load_dword v16, v14, s[8:9] offset:256
	v_readlane_b32 s8, v255, 11
	v_readlane_b32 s9, v255, 12
	ds_bpermute_b32 v210, v197, v201
	s_waitcnt vmcnt(1)
	v_max_f32_e64 v15, |v15|, |v15|
	s_waitcnt vmcnt(0)
	v_max_f32_e64 v16, |v16|, |v16|
	v_max_f32_e32 v15, v15, v16
	global_load_dword v16, v14, s[8:9]
	global_load_dword v17, v14, s[8:9] offset:256
	s_lshl_b64 s[8:9], s[4:5], 2
	s_add_u32 s8, s2, s8
	s_addc_u32 s9, s3, s9
	s_lshl_b32 s5, s6, 2
	s_add_i32 s15, s5, 4
	v_cmp_gt_u32_e32 vcc, s15, v208
	s_waitcnt vmcnt(1)
	v_max_f32_e64 v16, |v16|, |v16|
	s_waitcnt vmcnt(0)
	v_max_f32_e64 v17, |v17|, |v17|
	v_max_f32_e32 v16, v16, v17
	v_xor_b32_e32 v17, 4, v14
	ds_bpermute_b32 v18, v17, v15
	ds_bpermute_b32 v17, v17, v16
	s_waitcnt lgkmcnt(1)
	v_max_f32_e32 v18, v18, v18
	s_waitcnt lgkmcnt(0)
	v_max_f32_e32 v17, v17, v17
	v_max_f32_e32 v15, v15, v18
	v_max_f32_e32 v16, v16, v17
	v_xor_b32_e32 v17, 8, v14
	ds_bpermute_b32 v18, v17, v15
	ds_bpermute_b32 v17, v17, v16
	s_waitcnt lgkmcnt(1)
	v_max_f32_e32 v18, v18, v18
	s_waitcnt lgkmcnt(0)
	v_max_f32_e32 v17, v17, v17
	v_max_f32_e32 v15, v15, v18
	v_max_f32_e32 v16, v16, v17
	v_xor_b32_e32 v17, 16, v14
	ds_bpermute_b32 v18, v17, v15
	ds_bpermute_b32 v17, v17, v16
	s_waitcnt lgkmcnt(1)
	v_max_f32_e32 v18, v18, v18
	s_waitcnt lgkmcnt(0)
	v_max_f32_e32 v17, v17, v17
	v_max_f32_e32 v15, v15, v18
	v_max_f32_e32 v16, v16, v17
	v_xor_b32_e32 v17, 32, v14
	ds_bpermute_b32 v18, v17, v15
	ds_bpermute_b32 v17, v17, v16
	v_xor_b32_e32 v14, 64, v14
	s_waitcnt lgkmcnt(1)
	v_max_f32_e32 v18, v18, v18
	v_max_f32_e32 v15, v15, v18
	s_waitcnt lgkmcnt(0)
	v_max_f32_e32 v17, v17, v17
	v_max_f32_e32 v16, v16, v17
	ds_bpermute_b32 v17, v14, v15
	ds_bpermute_b32 v14, v14, v16
	s_waitcnt lgkmcnt(1)
	v_max_f32_e32 v17, v17, v17
	v_max_f32_e32 v15, v15, v17
	s_waitcnt lgkmcnt(0)
	v_max_f32_e32 v14, v14, v14
	v_max_f32_e32 v14, v16, v14
	ds_bpermute_b32 v16, v197, v15
	s_waitcnt lgkmcnt(0)
	v_max_f32_e32 v16, v16, v16
	v_max_f32_e32 v15, v15, v16
	ds_bpermute_b32 v16, v197, v14
	v_mul_f32_e32 v15, 0x4185307d, v15
	s_waitcnt lgkmcnt(0)
	v_max_f32_e32 v16, v16, v16
	v_max_f32_e32 v14, v14, v16
	v_mul_f32_e32 v190, v14, v15
	global_load_dword v14, v1, s[8:9]
	s_mov_b64 s[8:9], 0
	s_waitcnt vmcnt(0)
	v_fmac_f32_e32 v14, -2.0, v190
	v_add_f32_e32 v14, 0xc2000000, v14
	s_and_saveexec_b64 s[12:13], vcc
	s_cbranch_execz .LBB0_526
	v_lshlrev_b32_e32 v15, 8, v208
	global_load_dword v15, v15, s[2:3] offset:252
	s_waitcnt vmcnt(0)
	v_cmp_lt_f32_e32 vcc, v15, v14
	s_and_b64 s[10:11], vcc, exec
